# EpiProj stores: SGPR base + 32-bit VGPR offset + immediate (no per-group 64-bit VALU address math), two data register sets with the store one group behind
# baseline (speedup 1.0000x reference)
; #define PG8_LAS __attribute__((address_space(3)))
; __device__ __forceinline__ unsigned cvt_pk_bf16(float lo, float hi) { unsigned r; asm volatile("v_cvt_pk_bf16_f32 %0, %1, %2" : "=v"(r) : "v"(lo), "v"(hi)); return r; }
;     __device__ __forceinline__ void operator()(const f32x4 (&acc)[2][2][4][2], const Unit& u, int wr, int wc, int fr, int fq) const {
;     ...
;                 for (int bj = 0; bj < 2; ++bj) { const f32x4 v0 = acc[ai][bj][m][0], v1 = acc[ai][bj][m][1];
;                     u32x4 w; w.x = cvt_pk_bf16(v0[0], v0[1]); w.y = cvt_pk_bf16(v0[2], v0[3]); w.z = cvt_pk_bf16(v1[0], v1[1]); w.w = cvt_pk_bf16(v1[2], v1[3]);
;                     PG8_LAS unsigned char* tl = epl + (wr * 4 + wc) * 2048 + ((ai * 4 + m) * 2 + bj) % 2 * 1024;
;                     const int ln = fq * 16 + fr;
;                     *(PG8_LAS u32x4*)(tl + fr * 64 + ((fq ^ (fr >> 2)) & 3) * 16) = w;
;                     const int r2 = ln >> 2, p2 = ln & 3;
;                     const u32x4 w2 = *(const PG8_LAS u32x4*)(tl + r2 * 64 + ((p2 ^ (r2 >> 2)) & 3) * 16);
;                     const int cc = u.pn * BM + bj * HALF + wc * 32;
;                     bf16_t* dst = O + ((size_t)(cc >> 6) * 16384 + (size_t)(u.pm * BM + wr * 64 + ai * HALF + m * 16 + r2)) * 64 + (cc & 63) + p2 * 8;
;                     *(u32x4*)dst = w2; } }
.LBB0_178:
	s_lshl_b32 s31, s64, 8
	s_or_b32 s31, s31, s60
	s_ashr_i32 s48, s31, 6
	s_ashr_i32 s49, s48, 31
	s_lshl_b64 s[46:47], s[48:49], 21
	s_add_u32 s46, s10, s46
	s_addc_u32 s47, s11, s47
	s_lshl_b32 s31, s65, 15
	s_add_u32 s46, s46, s31
	s_addc_u32 s47, s47, 0
	s_add_u32 s46, s46, s34
	s_addc_u32 s47, s47, s35
	s_add_u32 s48, s46, 0x400000
	s_addc_u32 s49, s47, 0
	v_lshl_add_u32 v144, v147, 7, v188
	v_add_u32_e32 v145, 0x1000, v144
	v_cvt_pk_bf16_f32 v154, v128, v129
	v_cvt_pk_bf16_f32 v155, v130, v131
	v_cvt_pk_bf16_f32 v156, v124, v125
	v_cvt_pk_bf16_f32 v157, v126, v127
	ds_write_b128 v152, v[154:157]
	ds_read_b128 v[154:157], v153
	v_cvt_pk_bf16_f32 v158, v116, v117
	v_cvt_pk_bf16_f32 v159, v118, v119
	v_cvt_pk_bf16_f32 v160, v108, v109
	v_cvt_pk_bf16_f32 v161, v110, v111
	ds_write_b128 v152, v[158:161] offset:1024
	ds_read_b128 v[158:161], v153 offset:1024
	s_waitcnt lgkmcnt(2)
	global_store_dwordx4 v144, v[154:157], s[46:47]
	s_nop 1
	v_cvt_pk_bf16_f32 v154, v120, v121
	v_cvt_pk_bf16_f32 v155, v122, v123
	v_cvt_pk_bf16_f32 v156, v112, v113
	v_cvt_pk_bf16_f32 v157, v114, v115
	ds_write_b128 v152, v[154:157]
	ds_read_b128 v[154:157], v153
	s_waitcnt lgkmcnt(2)
	global_store_dwordx4 v144, v[158:161], s[48:49]
	s_nop 1
	v_cvt_pk_bf16_f32 v158, v100, v101
	v_cvt_pk_bf16_f32 v159, v102, v103
	v_cvt_pk_bf16_f32 v160, v92, v93
	v_cvt_pk_bf16_f32 v161, v94, v95
	ds_write_b128 v152, v[158:161] offset:1024
	ds_read_b128 v[158:161], v153 offset:1024
	s_waitcnt lgkmcnt(2)
	global_store_dwordx4 v144, v[154:157], s[46:47] offset:2048
	s_nop 1
	v_cvt_pk_bf16_f32 v154, v104, v105
	v_cvt_pk_bf16_f32 v155, v106, v107
	v_cvt_pk_bf16_f32 v156, v96, v97
	v_cvt_pk_bf16_f32 v157, v98, v99
	ds_write_b128 v152, v[154:157]
	ds_read_b128 v[154:157], v153
	s_waitcnt lgkmcnt(2)
	global_store_dwordx4 v144, v[158:161], s[48:49] offset:2048
	s_nop 1
	v_cvt_pk_bf16_f32 v158, v84, v85
	v_cvt_pk_bf16_f32 v159, v86, v87
	v_cvt_pk_bf16_f32 v160, v76, v77
	v_cvt_pk_bf16_f32 v161, v78, v79
	ds_write_b128 v152, v[158:161] offset:1024
	ds_read_b128 v[158:161], v153 offset:1024
	s_waitcnt lgkmcnt(2)
	global_store_dwordx4 v145, v[154:157], s[46:47]
	s_nop 1
	v_cvt_pk_bf16_f32 v154, v88, v89
	v_cvt_pk_bf16_f32 v155, v90, v91
	v_cvt_pk_bf16_f32 v156, v80, v81
	v_cvt_pk_bf16_f32 v157, v82, v83
	ds_write_b128 v152, v[154:157]
	ds_read_b128 v[154:157], v153
	s_waitcnt lgkmcnt(2)
	global_store_dwordx4 v145, v[158:161], s[48:49]
	s_nop 1
	v_cvt_pk_bf16_f32 v158, v72, v73
	v_cvt_pk_bf16_f32 v159, v74, v75
	v_cvt_pk_bf16_f32 v160, v68, v69
	v_cvt_pk_bf16_f32 v161, v70, v71
	ds_write_b128 v152, v[158:161] offset:1024
	ds_read_b128 v[158:161], v153 offset:1024
	s_waitcnt lgkmcnt(2)
	global_store_dwordx4 v145, v[154:157], s[46:47] offset:2048
	s_nop 1
	v_cvt_pk_bf16_f32 v154, v64, v65
	v_cvt_pk_bf16_f32 v155, v66, v67
	v_cvt_pk_bf16_f32 v156, v60, v61
	v_cvt_pk_bf16_f32 v157, v62, v63
	ds_write_b128 v152, v[154:157]
	ds_read_b128 v[154:157], v153
	s_waitcnt lgkmcnt(2)
	global_store_dwordx4 v145, v[158:161], s[48:49] offset:2048
	s_add_u32 s46, s46, 0x4000
	s_addc_u32 s47, s47, 0
	s_add_u32 s48, s48, 0x4000
	s_addc_u32 s49, s49, 0
	v_cvt_pk_bf16_f32 v158, v52, v53
	v_cvt_pk_bf16_f32 v159, v54, v55
	v_cvt_pk_bf16_f32 v160, v44, v45
	v_cvt_pk_bf16_f32 v161, v46, v47
	ds_write_b128 v152, v[158:161] offset:1024
	ds_read_b128 v[158:161], v153 offset:1024
	s_waitcnt lgkmcnt(2)
	global_store_dwordx4 v144, v[154:157], s[46:47]
	s_nop 1
	v_cvt_pk_bf16_f32 v154, v56, v57
	v_cvt_pk_bf16_f32 v155, v58, v59
	v_cvt_pk_bf16_f32 v156, v48, v49
	v_cvt_pk_bf16_f32 v157, v50, v51
	ds_write_b128 v152, v[154:157]
	ds_read_b128 v[154:157], v153
	s_waitcnt lgkmcnt(2)
	global_store_dwordx4 v144, v[158:161], s[48:49]
	s_nop 1
	v_cvt_pk_bf16_f32 v158, v36, v37
	v_cvt_pk_bf16_f32 v159, v38, v39
	v_cvt_pk_bf16_f32 v160, v28, v29
	v_cvt_pk_bf16_f32 v161, v30, v31
	ds_write_b128 v152, v[158:161] offset:1024
	ds_read_b128 v[158:161], v153 offset:1024
	s_waitcnt lgkmcnt(2)
	global_store_dwordx4 v144, v[154:157], s[46:47] offset:2048
	s_nop 1
	v_cvt_pk_bf16_f32 v154, v40, v41
	v_cvt_pk_bf16_f32 v155, v42, v43
	v_cvt_pk_bf16_f32 v156, v32, v33
	v_cvt_pk_bf16_f32 v157, v34, v35
	ds_write_b128 v152, v[154:157]
	ds_read_b128 v[154:157], v153
	s_waitcnt lgkmcnt(2)
	global_store_dwordx4 v144, v[158:161], s[48:49] offset:2048
	s_nop 1
	v_cvt_pk_bf16_f32 v158, v20, v21
	v_cvt_pk_bf16_f32 v159, v22, v23
	v_cvt_pk_bf16_f32 v160, v12, v13
	v_cvt_pk_bf16_f32 v161, v14, v15
	ds_write_b128 v152, v[158:161] offset:1024
	ds_read_b128 v[158:161], v153 offset:1024
	s_waitcnt lgkmcnt(2)
	global_store_dwordx4 v145, v[154:157], s[46:47]
	s_nop 1
	v_cvt_pk_bf16_f32 v154, v24, v25
	v_cvt_pk_bf16_f32 v155, v26, v27
	v_cvt_pk_bf16_f32 v156, v16, v17
	v_cvt_pk_bf16_f32 v157, v18, v19
	ds_write_b128 v152, v[154:157]
	ds_read_b128 v[154:157], v153
	s_waitcnt lgkmcnt(2)
	global_store_dwordx4 v145, v[158:161], s[48:49]
	s_nop 1
	v_cvt_pk_bf16_f32 v158, v8, v9
	v_cvt_pk_bf16_f32 v159, v10, v11
	v_cvt_pk_bf16_f32 v160, v4, v5
	v_cvt_pk_bf16_f32 v161, v6, v7
	ds_write_b128 v152, v[158:161] offset:1024
	ds_read_b128 v[158:161], v153 offset:1024
	s_waitcnt lgkmcnt(2)
	global_store_dwordx4 v145, v[154:157], s[46:47] offset:2048
	s_nop 1
	s_waitcnt lgkmcnt(0)
	global_store_dwordx4 v145, v[158:161], s[48:49] offset:2048
	v_readlane_b32 s75, v255, 25
	s_mov_b32 s89, 0x2aaaaaab
	s_cmp_lt_i32 s64, 5
	s_cbranch_scc1 .LBB0_181
	v_readlane_b32 s94, v255, 33
	v_readlane_b32 s96, v255, 19
	s_cmp_gt_i32 s64, 12
	v_readlane_b32 s95, v255, 34
	v_readlane_b32 s97, v255, 20
	s_cbranch_scc0 .LBB0_182
	s_cmp_eq_u32 s64, 13
	s_cselect_b64 s[46:47], -1, 0
	s_cbranch_execz .LBB0_183
	s_branch .LBB0_184
